# attention softmax scale FMAs: 19 eligible v_fmamk pairs per two tiles converted to v_pk_fma_f32 (same single-rounding fma)
# baseline (speedup 1.0000x reference)
; __device__ __forceinline__ void partialSM(f32x16& p0, f32x16& p1, float& m_reg, float& mn, float& alpha) {
;     ...
;     const float mnL = -mn * C2;
; #pragma unroll
;     for (int r = 0; r < 16; ++r) p0[r] = fmaf(p0[r], C2, mnL);
; #pragma unroll
;     for (int r = 0; r < 16; ++r) p1[r] = fmaf(p1[r], C2, mnL);
; #pragma unroll
;     for (int r = 0; r < 16; ++r) p0[r] = __builtin_amdgcn_exp2f(p0[r]);
; __device__ __forceinline__ void finishSM(f32x16& p0, f32x16& p1, float alpha, float& l_reg, bf16x8& pa0, bf16x8& pa1, bf16x8& pa2, bf16x8& pa3) {
;     ...
;     l_reg = l_reg * alpha + ps;
.LBB0_1480:
	v_cndmask_b32_e64 v208, v147, v208, s[42:43]
	v_mul_f32_e32 v148, 0xbdd53b94, v208
	v_mov_b32_e32 v147, v148
	v_pk_fma_f32 v[112:113], v[112:113], s[18:19], v[148:149] op_sel_hi:[1,0,0]
	v_pk_fma_f32 v[114:115], v[114:115], s[18:19], v[148:149] op_sel_hi:[1,0,0]
	v_pk_fma_f32 v[116:117], v[116:117], s[18:19], v[148:149] op_sel_hi:[1,0,0]
	v_pk_fma_f32 v[118:119], v[118:119], s[18:19], v[148:149] op_sel_hi:[1,0,0]
	v_pk_fma_f32 v[120:121], v[120:121], s[18:19], v[148:149] op_sel_hi:[1,0,0]
	v_pk_fma_f32 v[122:123], v[122:123], s[18:19], v[148:149] op_sel_hi:[1,0,0]
	v_pk_fma_f32 v[124:125], v[124:125], s[18:19], v[148:149] op_sel_hi:[1,0,0]
	v_fmamk_f32 v126, v126, 0x3dd53b94, v148
	v_fmac_f32_e32 v147, 0x3dd53b94, v127
	v_exp_f32_e32 v233, v112
	v_exp_f32_e32 v235, v113
	v_exp_f32_e32 v231, v114
	v_exp_f32_e32 v234, v115
	v_exp_f32_e32 v223, v116
	v_exp_f32_e32 v232, v117
	v_exp_f32_e32 v221, v118
	v_exp_f32_e32 v222, v119
	v_exp_f32_e32 v217, v120
	v_exp_f32_e32 v220, v121
	v_exp_f32_e32 v215, v122
	v_exp_f32_e32 v218, v123
	v_exp_f32_e32 v213, v124
	v_exp_f32_e32 v219, v125
	v_exp_f32_e32 v214, v126
	v_exp_f32_e32 v216, v147
	v_pk_fma_f32 v[180:181], v[96:97], s[18:19], v[148:149] op_sel_hi:[1,0,0]
	v_add_f32_e32 v96, v210, v211
	v_fmac_f32_e32 v96, v203, v205
	v_add_f32_e32 v205, v236, v237
	s_addk_i32 s31, 0x80
	s_add_i32 s26, s26, 2
	v_pk_fma_f32 v[166:167], v[110:111], s[18:19], v[148:149] op_sel_hi:[1,0,0]
	v_pk_fma_f32 v[168:169], v[108:109], s[18:19], v[148:149] op_sel_hi:[1,0,0]
	v_pk_fma_f32 v[170:171], v[106:107], s[18:19], v[148:149] op_sel_hi:[1,0,0]
	v_pk_fma_f32 v[172:173], v[104:105], s[18:19], v[148:149] op_sel_hi:[1,0,0]
	v_pk_fma_f32 v[174:175], v[102:103], s[18:19], v[148:149] op_sel_hi:[1,0,0]
	v_pk_fma_f32 v[176:177], v[100:101], s[18:19], v[148:149] op_sel_hi:[1,0,0]
	v_pk_fma_f32 v[178:179], v[98:99], s[18:19], v[148:149] op_sel_hi:[1,0,0]
	v_fmac_f32_e32 v205, v96, v212
	s_cmp_ge_u32 s26, s35
	v_add_u32_e32 v209, 0xffffff80, v209
	v_mov_b32_e32 v203, v146
	s_waitcnt lgkmcnt(0)
	s_barrier
	s_cbranch_scc1 .LBB0_1497

; __device__ __forceinline__ void partialSM(f32x16& p0, f32x16& p1, float& m_reg, float& mn, float& alpha) {
;     ...
;     constexpr float C2 = 1.4426950408889634f * SCALE;
;     if (__builtin_expect(__all((pmax - m_reg) * SCALE <= THR), 1)) { mn = m_reg; alpha = 1.f; }
;     else { mn = fmaxf(m_reg, pmax); alpha = __builtin_amdgcn_exp2f((m_reg - mn) * C2); m_reg = mn; }
;     const float mnL = -mn * C2;
; #pragma unroll
;     for (int r = 0; r < 16; ++r) p0[r] = fmaf(p0[r], C2, mnL);
; #pragma unroll
;     for (int r = 0; r < 16; ++r) p1[r] = fmaf(p1[r], C2, mnL);
; #pragma unroll
;     for (int r = 0; r < 16; ++r) p0[r] = __builtin_amdgcn_exp2f(p0[r]);
.LBB0_1487:
	v_cndmask_b32_e64 v208, v64, v208, s[42:43]
	v_mul_f32_e32 v166, 0xbdd53b94, v208
	v_pk_fma_f32 v[64:65], v[84:85], s[18:19], v[166:167] op_sel_hi:[1,0,0]
	v_pk_fma_f32 v[66:67], v[86:87], s[18:19], v[166:167] op_sel_hi:[1,0,0]
	v_pk_fma_f32 v[100:101], v[88:89], s[18:19], v[166:167] op_sel_hi:[1,0,0]
	v_pk_fma_f32 v[102:103], v[90:91], s[18:19], v[166:167] op_sel_hi:[1,0,0]
	v_pk_fma_f32 v[104:105], v[92:93], s[18:19], v[166:167] op_sel_hi:[1,0,0]
	v_pk_fma_f32 v[106:107], v[94:95], s[18:19], v[166:167] op_sel_hi:[1,0,0]
	v_pk_fma_f32 v[96:97], v[96:97], s[18:19], v[166:167] op_sel_hi:[1,0,0]
	v_pk_fma_f32 v[98:99], v[98:99], s[18:19], v[166:167] op_sel_hi:[1,0,0]
	v_fmamk_f32 v84, v68, 0x3dd53b94, v166
	v_fmamk_f32 v93, v69, 0x3dd53b94, v166
	v_pk_fma_f32 v[94:95], v[70:71], s[18:19], v[166:167] op_sel_hi:[1,0,0]
	v_fmamk_f32 v167, v72, 0x3dd53b94, v166
	v_fmamk_f32 v85, v73, 0x3dd53b94, v166
	v_pk_fma_f32 v[86:87], v[74:75], s[18:19], v[166:167] op_sel_hi:[1,0,0]
	v_pk_fma_f32 v[88:89], v[76:77], s[18:19], v[166:167] op_sel_hi:[1,0,0]
	v_pk_fma_f32 v[90:91], v[78:79], s[18:19], v[166:167] op_sel_hi:[1,0,0]
	v_exp_f32_e32 v64, v64
	v_exp_f32_e32 v65, v65
	v_exp_f32_e32 v66, v66
	v_exp_f32_e32 v67, v67
	v_exp_f32_e32 v68, v100
	v_exp_f32_e32 v69, v101
	v_exp_f32_e32 v70, v102
	v_exp_f32_e32 v71, v103
	v_exp_f32_e32 v72, v104
	v_exp_f32_e32 v73, v105
	v_exp_f32_e32 v74, v106
	v_exp_f32_e32 v75, v107
	v_exp_f32_e32 v76, v96
	v_exp_f32_e32 v77, v97
	v_exp_f32_e32 v78, v98
	v_exp_f32_e32 v79, v99
	v_fmamk_f32 v92, v80, 0x3dd53b94, v166
	v_fmamk_f32 v168, v81, 0x3dd53b94, v166
	v_fmamk_f32 v169, v82, 0x3dd53b94, v166
	v_fmac_f32_e32 v166, 0x3dd53b94, v83
	s_waitcnt lgkmcnt(0)
	s_barrier
	ds_read_b128 v[80:83], v202 offset:45568
	ds_read_b128 v[96:99], v202 offset:32768
	ds_read_b128 v[170:173], v202 offset:32800
	s_add_i32 s0, s26, 1
	s_cmp_lt_u32 s0, s35
	s_cselect_b64 s[28:29], -1, 0
	s_cmp_ge_u32 s0, s35
	s_cbranch_scc1 .La_s3skip2
	v_add_u32_e32 v146, 0xc0, v254
	v_min_u32_e32 v148, 0x100f, v146
	v_add_u32_e32 v147, 0x40c0, v254
	v_add_u32_e32 v148, s14, v148
	v_cmp_gt_i32_e32 vcc, 16, v146
	s_nop 1
	v_cndmask_b32_e32 v146, v148, v147, vcc
	v_ashrrev_i32_e32 v147, 31, v146
	v_mad_i64_i32 v[158:159], s[0:1], v146, s33, v[184:185]
	v_lshlrev_b64 v[146:147], 12, v[146:147]
	v_lshl_add_u64 v[160:161], v[186:187], 0, v[146:147]
	global_load_dwordx4 v[146:149], v[160:161], off offset:128
	global_load_dwordx4 v[150:153], v[158:159], off
	global_load_dwordx4 v[154:157], v[158:159], off offset:128
	global_load_dwordx4 v[162:165], v[160:161], off
	s_nop 0
	global_load_dwordx4 v[158:161], v[158:159], off offset:256
